# FFN1 tile end: drop vmcnt(0) store drain before the tile barrier (next tile's counted waits cover it) so store acks overlap tile setup
# baseline (speedup 1.0000x reference)
; DI float dppx1(float v) { return __int_as_float(__builtin_amdgcn_update_dpp(0, __float_as_int(v), 0xB1, 0xF, 0xF, true)); }
; DI void store_pair_bf16(u16* base_even, long ld, bool odd, float v0, float v1, float v2, float v3) {
;   const float sx = odd ? v0 : v2, sy = odd ? v1 : v3;
;   const float rx = dppx1(sx), ry = dppx1(sy);
;   const uint32_t p0 = odd ? pack2(rx, v2) : pack2(v0, rx);
;   const uint32_t p1 = odd ? pack2(ry, v3) : pack2(v1, ry);
;   u16* q = base_even + (odd ? 2 * ld : 0);
;   *(uint32_t*)q = p0;
;   *(uint32_t*)(q + ld) = p1;
; }
; __global__ void __launch_bounds__(NTHR) fwd_kernel(Params pk) {
;     ...
;         auto epi = [&](int pm, int pn, Acc8& acc, int wr, int wc, int fr, int fq) {
; #pragma unroll
;           for (int ai = 0; ai < 2; ++ai)
; #pragma unroll
;             for (int bj = 0; bj < 2; ++bj)
; #pragma unroll
;               for (int m = 0; m < 4; ++m)
;                 {
;                   float v[4];
; #pragma unroll
;                   for (int j = 0; j < 4; ++j) {
;                     float a = acc[ai][bj][m][0][j], b = acc[ai][bj][m][1][j];
;                     v[j] = a * __builtin_amdgcn_rcpf(1.f + __expf(-a)) * b;
;                   }
;                   const long row0 = (long)pm * 256 + ai * 128 + wr * 64 + m * 16 + fq * 4;
;                   const int cole = pn * 128 + (bj * 4 + wc) * 16 + (fr & ~1);
;                   store_pair_bf16(act + row0 * DFF + cole, DFF, fr & 1, v[0], v[1], v[2], v[3]);
;                 }
;         };
.LBB0_143:
	s_ashr_i32 s65, s64, 31
	s_lshl_b64 s[4:5], s[64:65], 8
	v_ashrrev_i32_e32 v133, 31, v132
	v_lshl_add_u64 v[130:131], s[4:5], 0, v[132:133]
	s_lshl_b32 s3, s8, 7
	v_lshlrev_b32_e32 v128, 4, v146
	v_and_b32_e32 v132, 14, v138
	v_or3_b32 v132, v128, s3, v132
	v_and_b32_e32 v128, 1, v138
	v_bfe_i32 v133, v138, 0, 1
	v_cmp_eq_u32_e32 vcc, 0, v128
	v_and_b32_e32 v128, 0x2c00, v133
	v_lshl_add_u64 v[134:135], s[14:15], 0, v[128:129]
	v_mul_f32_e32 v128, 0xbfb8aa3b, v120
	v_exp_f32_e32 v128, v128
	v_ashrrev_i32_e32 v133, 31, v132
	v_lshl_or_b32 v130, v147, 2, v130
	v_lshl_add_u64 v[132:133], v[132:133], 1, v[134:135]
	v_add_f32_e32 v128, 1.0, v128
	v_rcp_f32_e32 v128, v128
	s_mov_b32 s3, 0x16000
	s_mov_b64 s[68:69], 0
	s_mov_b32 s64, s54
	v_mul_f32_e32 v120, v120, v128
	v_mul_f32_e32 v120, v124, v120
	v_mul_f32_e32 v124, 0xbfb8aa3b, v121
	v_exp_f32_e32 v124, v124
	s_nop 0
	v_add_f32_e32 v124, 1.0, v124
	v_rcp_f32_e32 v124, v124
	s_nop 0
	v_mul_f32_e32 v121, v121, v124
	v_mul_f32_e32 v124, 0xbfb8aa3b, v122
	v_exp_f32_e32 v124, v124
	v_mul_f32_e32 v121, v125, v121
	v_add_f32_e32 v124, 1.0, v124
	v_rcp_f32_e32 v124, v124
	s_nop 0
	v_mul_f32_e32 v122, v122, v124
	v_mul_f32_e32 v124, 0xbfb8aa3b, v123
	v_exp_f32_e32 v124, v124
	v_mul_f32_e32 v122, v126, v122
	v_add_f32_e32 v124, 1.0, v124
	v_rcp_f32_e32 v124, v124
	s_nop 0
	v_mul_f32_e32 v123, v123, v124
	v_mul_f32_e32 v123, v127, v123
	v_cndmask_b32_e32 v124, v120, v122, vcc
	v_cndmask_b32_e32 v125, v121, v123, vcc
	s_nop 0
	v_mov_b32_dpp v124, v124 quad_perm:[1,0,3,2] row_mask:0xf bank_mask:0xf bound_ctrl:1
	v_mov_b32_dpp v125, v125 quad_perm:[1,0,3,2] row_mask:0xf bank_mask:0xf bound_ctrl:1
	v_cndmask_b32_e32 v122, v122, v124, vcc
	v_cndmask_b32_e32 v120, v124, v120, vcc
	v_cndmask_b32_e32 v123, v123, v125, vcc
	v_cndmask_b32_e32 v121, v125, v121, vcc
	v_cvt_pk_bf16_f32 v124, v121, v123
	v_cvt_pk_bf16_f32 v122, v120, v122
	v_mad_u64_u32 v[120:121], s[4:5], v130, s72, v[132:133]
	v_mad_i32_i24 v121, v131, s72, v121
	global_store_dword v[120:121], v122, off
	v_add_co_u32_e64 v122, s[8:9], s7, v120
	s_nop 1
	v_addc_co_u32_e64 v123, s[8:9], 0, v121, s[8:9]
	global_store_dword v[122:123], v124, off offset:1536
	v_mul_f32_e32 v124, 0xbfb8aa3b, v112
	v_exp_f32_e32 v124, v124
	s_nop 0
	v_add_f32_e32 v124, 1.0, v124
	v_rcp_f32_e32 v124, v124
	s_nop 0
	v_mul_f32_e32 v112, v112, v124
	v_mul_f32_e32 v112, v116, v112
	v_mul_f32_e32 v116, 0xbfb8aa3b, v113
	v_exp_f32_e32 v116, v116
	s_nop 0
	v_add_f32_e32 v116, 1.0, v116
	v_rcp_f32_e32 v116, v116
	s_nop 0
	v_mul_f32_e32 v113, v113, v116
	v_mul_f32_e32 v116, 0xbfb8aa3b, v114
	v_exp_f32_e32 v116, v116
	v_mul_f32_e32 v113, v117, v113
	v_add_f32_e32 v116, 1.0, v116
	v_rcp_f32_e32 v116, v116
	s_nop 0
	v_mul_f32_e32 v114, v114, v116
	v_mul_f32_e32 v116, 0xbfb8aa3b, v115
	v_exp_f32_e32 v116, v116
	v_mul_f32_e32 v114, v118, v114
	v_add_f32_e32 v116, 1.0, v116
	v_rcp_f32_e32 v116, v116
	s_nop 0
	v_mul_f32_e32 v115, v115, v116
	v_mul_f32_e32 v115, v119, v115
	v_cndmask_b32_e32 v116, v112, v114, vcc
	v_cndmask_b32_e32 v117, v113, v115, vcc
	s_nop 0
	v_mov_b32_dpp v116, v116 quad_perm:[1,0,3,2] row_mask:0xf bank_mask:0xf bound_ctrl:1
	v_mov_b32_dpp v117, v117 quad_perm:[1,0,3,2] row_mask:0xf bank_mask:0xf bound_ctrl:1
	v_cndmask_b32_e32 v114, v114, v116, vcc
	v_cndmask_b32_e32 v112, v116, v112, vcc
	v_cndmask_b32_e32 v115, v115, v117, vcc
	v_cndmask_b32_e32 v113, v117, v113, vcc
	v_cvt_pk_bf16_f32 v114, v112, v114
	v_add_co_u32_e64 v112, s[8:9], s3, v120
	v_cvt_pk_bf16_f32 v116, v113, v115
	s_nop 0
	v_addc_co_u32_e64 v113, s[8:9], 0, v121, s[8:9]
	global_store_dword v[112:113], v114, off
	v_add_co_u32_e64 v114, s[8:9], s73, v120
	s_nop 1
	v_addc_co_u32_e64 v115, s[8:9], 0, v121, s[8:9]
	global_store_dword v[114:115], v116, off offset:1536
	v_mul_f32_e32 v116, 0xbfb8aa3b, v104
	v_exp_f32_e32 v116, v116
	s_nop 0
	v_add_f32_e32 v116, 1.0, v116
	v_rcp_f32_e32 v116, v116
	s_nop 0
	v_mul_f32_e32 v104, v104, v116
	v_mul_f32_e32 v104, v108, v104
	v_mul_f32_e32 v108, 0xbfb8aa3b, v105
	v_exp_f32_e32 v108, v108
	s_nop 0
	v_add_f32_e32 v108, 1.0, v108
	v_rcp_f32_e32 v108, v108
	s_nop 0
	v_mul_f32_e32 v105, v105, v108
	v_mul_f32_e32 v108, 0xbfb8aa3b, v106
	v_exp_f32_e32 v108, v108
	v_mul_f32_e32 v105, v109, v105
	v_add_f32_e32 v108, 1.0, v108
	v_rcp_f32_e32 v108, v108
	s_nop 0
	v_mul_f32_e32 v106, v106, v108
	v_mul_f32_e32 v108, 0xbfb8aa3b, v107
	v_exp_f32_e32 v108, v108
	v_mul_f32_e32 v106, v110, v106
	v_add_f32_e32 v108, 1.0, v108
	v_rcp_f32_e32 v108, v108
	s_nop 0
	v_mul_f32_e32 v107, v107, v108
	v_mul_f32_e32 v107, v111, v107
	v_cndmask_b32_e32 v108, v104, v106, vcc
	v_cndmask_b32_e32 v109, v105, v107, vcc
	s_nop 0
	v_mov_b32_dpp v108, v108 quad_perm:[1,0,3,2] row_mask:0xf bank_mask:0xf bound_ctrl:1
	v_mov_b32_dpp v109, v109 quad_perm:[1,0,3,2] row_mask:0xf bank_mask:0xf bound_ctrl:1
	v_cndmask_b32_e32 v106, v106, v108, vcc
	v_cndmask_b32_e32 v104, v108, v104, vcc
	v_cndmask_b32_e32 v107, v107, v109, vcc
	v_cndmask_b32_e32 v105, v109, v105, vcc
	v_cvt_pk_bf16_f32 v106, v104, v106
	v_add_co_u32_e64 v104, s[8:9], s74, v120
	v_cvt_pk_bf16_f32 v108, v105, v107
	s_nop 0
	v_addc_co_u32_e64 v105, s[8:9], 0, v121, s[8:9]
	global_store_dword v[104:105], v106, off
	v_add_co_u32_e64 v106, s[8:9], s75, v120
	s_nop 1
	v_addc_co_u32_e64 v107, s[8:9], 0, v121, s[8:9]
	global_store_dword v[106:107], v108, off offset:1536
	v_mul_f32_e32 v108, 0xbfb8aa3b, v96
	v_exp_f32_e32 v108, v108
	s_nop 0
	v_add_f32_e32 v108, 1.0, v108
	v_rcp_f32_e32 v108, v108
	s_nop 0
	v_mul_f32_e32 v96, v96, v108
	v_mul_f32_e32 v96, v100, v96
	v_mul_f32_e32 v100, 0xbfb8aa3b, v97
	v_exp_f32_e32 v100, v100
	s_nop 0
; DI float dppx1(float v) { return __int_as_float(__builtin_amdgcn_update_dpp(0, __float_as_int(v), 0xB1, 0xF, 0xF, true)); }
; DI void store_pair_bf16(u16* base_even, long ld, bool odd, float v0, float v1, float v2, float v3) {
;   const float sx = odd ? v0 : v2, sy = odd ? v1 : v3;
;   const float rx = dppx1(sx), ry = dppx1(sy);
;   const uint32_t p0 = odd ? pack2(rx, v2) : pack2(v0, rx);
;   const uint32_t p1 = odd ? pack2(ry, v3) : pack2(v1, ry);
;   u16* q = base_even + (odd ? 2 * ld : 0);
;   *(uint32_t*)q = p0;
;   *(uint32_t*)(q + ld) = p1;
; }
; __global__ void __launch_bounds__(NTHR) fwd_kernel(Params pk) {
;     ...
;         auto epi = [&](int pm, int pn, Acc8& acc, int wr, int wc, int fr, int fq) {
; #pragma unroll
;           for (int ai = 0; ai < 2; ++ai)
; #pragma unroll
;             for (int bj = 0; bj < 2; ++bj)
; #pragma unroll
;               for (int m = 0; m < 4; ++m)
;                 {
;                   float v[4];
; #pragma unroll
;                   for (int j = 0; j < 4; ++j) {
;                     float a = acc[ai][bj][m][0][j], b = acc[ai][bj][m][1][j];
;                     v[j] = a * __builtin_amdgcn_rcpf(1.f + __expf(-a)) * b;
;                   }
;                   const long row0 = (long)pm * 256 + ai * 128 + wr * 64 + m * 16 + fq * 4;
;                   const int cole = pn * 128 + (bj * 4 + wc) * 16 + (fr & ~1);
;                   store_pair_bf16(act + row0 * DFF + cole, DFF, fr & 1, v[0], v[1], v[2], v[3]);
;                 }
;         };
	v_add_f32_e32 v100, 1.0, v100
	v_rcp_f32_e32 v100, v100
	s_nop 0
	v_mul_f32_e32 v97, v97, v100
	v_mul_f32_e32 v100, 0xbfb8aa3b, v98
	v_exp_f32_e32 v100, v100
	v_mul_f32_e32 v97, v101, v97
	v_add_f32_e32 v100, 1.0, v100
	v_rcp_f32_e32 v100, v100
	s_nop 0
	v_mul_f32_e32 v98, v98, v100
	v_mul_f32_e32 v100, 0xbfb8aa3b, v99
	v_exp_f32_e32 v100, v100
	v_mul_f32_e32 v98, v102, v98
	v_add_f32_e32 v100, 1.0, v100
	v_rcp_f32_e32 v100, v100
	s_nop 0
	v_mul_f32_e32 v99, v99, v100
	v_mul_f32_e32 v99, v103, v99
	v_cndmask_b32_e32 v100, v96, v98, vcc
	v_cndmask_b32_e32 v101, v97, v99, vcc
	s_nop 0
	v_mov_b32_dpp v100, v100 quad_perm:[1,0,3,2] row_mask:0xf bank_mask:0xf bound_ctrl:1
	v_mov_b32_dpp v101, v101 quad_perm:[1,0,3,2] row_mask:0xf bank_mask:0xf bound_ctrl:1
	v_cndmask_b32_e32 v98, v98, v100, vcc
	v_cndmask_b32_e32 v96, v100, v96, vcc
	v_cndmask_b32_e32 v99, v99, v101, vcc
	v_cndmask_b32_e32 v97, v101, v97, vcc
	v_cvt_pk_bf16_f32 v98, v96, v98
	v_add_co_u32_e64 v96, s[8:9], s76, v120
	v_cvt_pk_bf16_f32 v100, v97, v99
	s_nop 0
	v_addc_co_u32_e64 v97, s[8:9], 0, v121, s[8:9]
	global_store_dword v[96:97], v98, off
	v_add_co_u32_e64 v98, s[8:9], s77, v120
	s_nop 1
	v_addc_co_u32_e64 v99, s[8:9], 0, v121, s[8:9]
	global_store_dword v[98:99], v100, off offset:1536
	v_mul_f32_e32 v100, 0xbfb8aa3b, v88
	v_exp_f32_e32 v100, v100
	s_nop 0
	v_add_f32_e32 v100, 1.0, v100
	v_rcp_f32_e32 v100, v100
	s_nop 0
	v_mul_f32_e32 v88, v88, v100
	v_mul_f32_e32 v88, v92, v88
	v_mul_f32_e32 v92, 0xbfb8aa3b, v89
	v_exp_f32_e32 v92, v92
	s_nop 0
	v_add_f32_e32 v92, 1.0, v92
	v_rcp_f32_e32 v92, v92
	s_nop 0
	v_mul_f32_e32 v89, v89, v92
	v_mul_f32_e32 v92, 0xbfb8aa3b, v90
	v_exp_f32_e32 v92, v92
	v_mul_f32_e32 v89, v93, v89
	v_add_f32_e32 v92, 1.0, v92
	v_rcp_f32_e32 v92, v92
	s_nop 0
	v_mul_f32_e32 v90, v90, v92
	v_mul_f32_e32 v92, 0xbfb8aa3b, v91
	v_exp_f32_e32 v92, v92
	v_mul_f32_e32 v90, v94, v90
	v_add_f32_e32 v92, 1.0, v92
	v_rcp_f32_e32 v92, v92
	s_nop 0
	v_mul_f32_e32 v91, v91, v92
	v_mul_f32_e32 v91, v95, v91
	v_cndmask_b32_e32 v92, v88, v90, vcc
	v_cndmask_b32_e32 v93, v89, v91, vcc
	s_nop 0
	v_mov_b32_dpp v92, v92 quad_perm:[1,0,3,2] row_mask:0xf bank_mask:0xf bound_ctrl:1
	v_mov_b32_dpp v93, v93 quad_perm:[1,0,3,2] row_mask:0xf bank_mask:0xf bound_ctrl:1
	v_cndmask_b32_e32 v90, v90, v92, vcc
	v_cndmask_b32_e32 v88, v92, v88, vcc
	v_cndmask_b32_e32 v91, v91, v93, vcc
	v_cndmask_b32_e32 v89, v93, v89, vcc
	v_cvt_pk_bf16_f32 v88, v88, v90
	v_cvt_pk_bf16_f32 v89, v89, v91
	global_store_dword v[120:121], v88, off offset:128
	global_store_dword v[122:123], v89, off offset:1664
	v_mul_f32_e32 v88, 0xbfb8aa3b, v80
	v_exp_f32_e32 v88, v88
	s_nop 0
	v_add_f32_e32 v88, 1.0, v88
	v_rcp_f32_e32 v88, v88
	s_nop 0
	v_mul_f32_e32 v80, v80, v88
	v_mul_f32_e32 v80, v84, v80
	v_mul_f32_e32 v84, 0xbfb8aa3b, v81
	v_exp_f32_e32 v84, v84
	s_nop 0
	v_add_f32_e32 v84, 1.0, v84
	v_rcp_f32_e32 v84, v84
	s_nop 0
	v_mul_f32_e32 v81, v81, v84
	v_mul_f32_e32 v84, 0xbfb8aa3b, v82
	v_exp_f32_e32 v84, v84
	v_mul_f32_e32 v81, v85, v81
	v_add_f32_e32 v84, 1.0, v84
	v_rcp_f32_e32 v84, v84
	s_nop 0
	v_mul_f32_e32 v82, v82, v84
	v_mul_f32_e32 v84, 0xbfb8aa3b, v83
	v_exp_f32_e32 v84, v84
	v_mul_f32_e32 v82, v86, v82
	v_add_f32_e32 v84, 1.0, v84
	v_rcp_f32_e32 v84, v84
	s_nop 0
	v_mul_f32_e32 v83, v83, v84
	v_mul_f32_e32 v83, v87, v83
	v_cndmask_b32_e32 v84, v80, v82, vcc
	v_cndmask_b32_e32 v85, v81, v83, vcc
	s_nop 0
	v_mov_b32_dpp v84, v84 quad_perm:[1,0,3,2] row_mask:0xf bank_mask:0xf bound_ctrl:1
	v_mov_b32_dpp v85, v85 quad_perm:[1,0,3,2] row_mask:0xf bank_mask:0xf bound_ctrl:1
	v_cndmask_b32_e32 v82, v82, v84, vcc
	v_cndmask_b32_e32 v80, v84, v80, vcc
	v_cndmask_b32_e32 v83, v83, v85, vcc
	v_cndmask_b32_e32 v81, v85, v81, vcc
	v_cvt_pk_bf16_f32 v80, v80, v82
	v_cvt_pk_bf16_f32 v81, v81, v83
	global_store_dword v[112:113], v80, off offset:128
	global_store_dword v[114:115], v81, off offset:1664
	v_mul_f32_e32 v80, 0xbfb8aa3b, v72
	v_exp_f32_e32 v80, v80
	s_nop 0
	v_add_f32_e32 v80, 1.0, v80
	v_rcp_f32_e32 v80, v80
	s_nop 0
	v_mul_f32_e32 v72, v72, v80
	v_mul_f32_e32 v72, v76, v72
	v_mul_f32_e32 v76, 0xbfb8aa3b, v73
	v_exp_f32_e32 v76, v76
	s_nop 0
	v_add_f32_e32 v76, 1.0, v76
	v_rcp_f32_e32 v76, v76
	s_nop 0
	v_mul_f32_e32 v73, v73, v76
	v_mul_f32_e32 v76, 0xbfb8aa3b, v74
	v_exp_f32_e32 v76, v76
	v_mul_f32_e32 v73, v77, v73
	v_add_f32_e32 v76, 1.0, v76
	v_rcp_f32_e32 v76, v76
	s_nop 0
	v_mul_f32_e32 v74, v74, v76
	v_mul_f32_e32 v76, 0xbfb8aa3b, v75
	v_exp_f32_e32 v76, v76
	v_mul_f32_e32 v74, v78, v74
	v_add_f32_e32 v76, 1.0, v76
	v_rcp_f32_e32 v76, v76
	s_nop 0
	v_mul_f32_e32 v75, v75, v76
	v_mul_f32_e32 v75, v79, v75
	v_cndmask_b32_e32 v76, v72, v74, vcc
	v_cndmask_b32_e32 v77, v73, v75, vcc
	s_nop 0
	v_mov_b32_dpp v76, v76 quad_perm:[1,0,3,2] row_mask:0xf bank_mask:0xf bound_ctrl:1
	v_mov_b32_dpp v77, v77 quad_perm:[1,0,3,2] row_mask:0xf bank_mask:0xf bound_ctrl:1
	v_cndmask_b32_e32 v74, v74, v76, vcc
	v_cndmask_b32_e32 v72, v76, v72, vcc
	v_cndmask_b32_e32 v75, v75, v77, vcc
	v_cndmask_b32_e32 v73, v77, v73, vcc
	v_cvt_pk_bf16_f32 v72, v72, v74
	v_cvt_pk_bf16_f32 v73, v73, v75
	global_store_dword v[104:105], v72, off offset:128
	global_store_dword v[106:107], v73, off offset:1664
	v_mul_f32_e32 v72, 0xbfb8aa3b, v64
	v_exp_f32_e32 v72, v72
	s_nop 0
	v_add_f32_e32 v72, 1.0, v72
	v_rcp_f32_e32 v72, v72
	s_nop 0
	v_mul_f32_e32 v64, v64, v72
	v_mul_f32_e32 v64, v68, v64
	v_mul_f32_e32 v68, 0xbfb8aa3b, v65
	v_exp_f32_e32 v68, v68
	s_nop 0
	v_add_f32_e32 v68, 1.0, v68
	v_rcp_f32_e32 v68, v68
	s_nop 0
	v_mul_f32_e32 v65, v65, v68
	v_mul_f32_e32 v68, 0xbfb8aa3b, v66
	v_exp_f32_e32 v68, v68
; DI float dppx1(float v) { return __int_as_float(__builtin_amdgcn_update_dpp(0, __float_as_int(v), 0xB1, 0xF, 0xF, true)); }
; DI void store_pair_bf16(u16* base_even, long ld, bool odd, float v0, float v1, float v2, float v3) {
;   const float sx = odd ? v0 : v2, sy = odd ? v1 : v3;
;   const float rx = dppx1(sx), ry = dppx1(sy);
;   const uint32_t p0 = odd ? pack2(rx, v2) : pack2(v0, rx);
;   const uint32_t p1 = odd ? pack2(ry, v3) : pack2(v1, ry);
;   u16* q = base_even + (odd ? 2 * ld : 0);
;   *(uint32_t*)q = p0;
;   *(uint32_t*)(q + ld) = p1;
; }
; __global__ void __launch_bounds__(NTHR) fwd_kernel(Params pk) {
;     ...
;         auto epi = [&](int pm, int pn, Acc8& acc, int wr, int wc, int fr, int fq) {
; #pragma unroll
;           for (int ai = 0; ai < 2; ++ai)
; #pragma unroll
;             for (int bj = 0; bj < 2; ++bj)
; #pragma unroll
;               for (int m = 0; m < 4; ++m)
;                 {
;                   float v[4];
; #pragma unroll
;                   for (int j = 0; j < 4; ++j) {
;                     float a = acc[ai][bj][m][0][j], b = acc[ai][bj][m][1][j];
;                     v[j] = a * __builtin_amdgcn_rcpf(1.f + __expf(-a)) * b;
;                   }
;                   const long row0 = (long)pm * 256 + ai * 128 + wr * 64 + m * 16 + fq * 4;
;                   const int cole = pn * 128 + (bj * 4 + wc) * 16 + (fr & ~1);
;                   store_pair_bf16(act + row0 * DFF + cole, DFF, fr & 1, v[0], v[1], v[2], v[3]);
;                 }
;         };
	v_mul_f32_e32 v65, v69, v65
	v_add_f32_e32 v68, 1.0, v68
	v_rcp_f32_e32 v68, v68
	s_nop 0
	v_mul_f32_e32 v66, v66, v68
	v_mul_f32_e32 v68, 0xbfb8aa3b, v67
	v_exp_f32_e32 v68, v68
	v_mul_f32_e32 v66, v70, v66
	v_add_f32_e32 v68, 1.0, v68
	v_rcp_f32_e32 v68, v68
	s_nop 0
	v_mul_f32_e32 v67, v67, v68
	v_mul_f32_e32 v67, v71, v67
	v_cndmask_b32_e32 v68, v64, v66, vcc
	v_cndmask_b32_e32 v69, v65, v67, vcc
	s_nop 0
	v_mov_b32_dpp v68, v68 quad_perm:[1,0,3,2] row_mask:0xf bank_mask:0xf bound_ctrl:1
	v_mov_b32_dpp v69, v69 quad_perm:[1,0,3,2] row_mask:0xf bank_mask:0xf bound_ctrl:1
	v_cndmask_b32_e32 v66, v66, v68, vcc
	v_cndmask_b32_e32 v64, v68, v64, vcc
	v_cndmask_b32_e32 v67, v67, v69, vcc
	v_cndmask_b32_e32 v65, v69, v65, vcc
	v_cvt_pk_bf16_f32 v64, v64, v66
	v_cvt_pk_bf16_f32 v65, v65, v67
	global_store_dword v[96:97], v64, off offset:128
	global_store_dword v[98:99], v65, off offset:1664
	v_mul_f32_e32 v64, 0xbfb8aa3b, v56
	v_exp_f32_e32 v64, v64
	s_nop 0
	v_add_f32_e32 v64, 1.0, v64
	v_rcp_f32_e32 v64, v64
	s_nop 0
	v_mul_f32_e32 v56, v56, v64
	v_mul_f32_e32 v56, v60, v56
	v_mul_f32_e32 v60, 0xbfb8aa3b, v57
	v_exp_f32_e32 v60, v60
	s_nop 0
	v_add_f32_e32 v60, 1.0, v60
	v_rcp_f32_e32 v60, v60
	s_nop 0
	v_mul_f32_e32 v57, v57, v60
	v_mul_f32_e32 v60, 0xbfb8aa3b, v58
	v_exp_f32_e32 v60, v60
	v_mul_f32_e32 v57, v61, v57
	v_add_f32_e32 v60, 1.0, v60
	v_rcp_f32_e32 v60, v60
	s_nop 0
	v_mul_f32_e32 v58, v58, v60
	v_mul_f32_e32 v60, 0xbfb8aa3b, v59
	v_exp_f32_e32 v60, v60
	v_mul_f32_e32 v58, v62, v58
	v_add_f32_e32 v60, 1.0, v60
	v_rcp_f32_e32 v60, v60
	s_nop 0
	v_mul_f32_e32 v59, v59, v60
	v_mul_f32_e32 v59, v63, v59
	v_cndmask_b32_e32 v60, v56, v58, vcc
	v_cndmask_b32_e32 v61, v57, v59, vcc
	s_nop 0
	v_mov_b32_dpp v60, v60 quad_perm:[1,0,3,2] row_mask:0xf bank_mask:0xf bound_ctrl:1
	v_mov_b32_dpp v61, v61 quad_perm:[1,0,3,2] row_mask:0xf bank_mask:0xf bound_ctrl:1
	v_cndmask_b32_e32 v58, v58, v60, vcc
	v_cndmask_b32_e32 v56, v60, v56, vcc
	v_cndmask_b32_e32 v59, v59, v61, vcc
	v_cndmask_b32_e32 v57, v61, v57, vcc
	v_cvt_pk_bf16_f32 v58, v56, v58
	v_add_co_u32_e64 v56, s[8:9], s80, v120
	v_cvt_pk_bf16_f32 v60, v57, v59
	s_nop 0
	v_addc_co_u32_e64 v57, s[8:9], 0, v121, s[8:9]
	global_store_dword v[56:57], v58, off
	v_add_co_u32_e64 v58, s[8:9], s81, v120
	s_nop 1
	v_addc_co_u32_e64 v59, s[8:9], 0, v121, s[8:9]
	global_store_dword v[58:59], v60, off offset:1536
	v_mul_f32_e32 v60, 0xbfb8aa3b, v48
	v_exp_f32_e32 v60, v60
	s_nop 0
	v_add_f32_e32 v60, 1.0, v60
	v_rcp_f32_e32 v60, v60
	s_nop 0
	v_mul_f32_e32 v48, v48, v60
	v_mul_f32_e32 v48, v52, v48
	v_mul_f32_e32 v52, 0xbfb8aa3b, v49
	v_exp_f32_e32 v52, v52
	s_nop 0
	v_add_f32_e32 v52, 1.0, v52
	v_rcp_f32_e32 v52, v52
	s_nop 0
	v_mul_f32_e32 v49, v49, v52
	v_mul_f32_e32 v52, 0xbfb8aa3b, v50
	v_exp_f32_e32 v52, v52
	v_mul_f32_e32 v49, v53, v49
	v_add_f32_e32 v52, 1.0, v52
	v_rcp_f32_e32 v52, v52
	s_nop 0
	v_mul_f32_e32 v50, v50, v52
	v_mul_f32_e32 v52, 0xbfb8aa3b, v51
	v_exp_f32_e32 v52, v52
	v_mul_f32_e32 v50, v54, v50
	v_add_f32_e32 v52, 1.0, v52
	v_rcp_f32_e32 v52, v52
	s_nop 0
	v_mul_f32_e32 v51, v51, v52
	v_mul_f32_e32 v51, v55, v51
	v_cndmask_b32_e32 v52, v48, v50, vcc
	v_cndmask_b32_e32 v53, v49, v51, vcc
	s_nop 0
	v_mov_b32_dpp v52, v52 quad_perm:[1,0,3,2] row_mask:0xf bank_mask:0xf bound_ctrl:1
	v_mov_b32_dpp v53, v53 quad_perm:[1,0,3,2] row_mask:0xf bank_mask:0xf bound_ctrl:1
	v_cndmask_b32_e32 v50, v50, v52, vcc
	v_cndmask_b32_e32 v48, v52, v48, vcc
	v_cndmask_b32_e32 v51, v51, v53, vcc
	v_cndmask_b32_e32 v49, v53, v49, vcc
	v_cvt_pk_bf16_f32 v50, v48, v50
	v_add_co_u32_e64 v48, s[8:9], s82, v120
	v_cvt_pk_bf16_f32 v52, v49, v51
	s_nop 0
	v_addc_co_u32_e64 v49, s[8:9], 0, v121, s[8:9]
	global_store_dword v[48:49], v50, off
	v_add_co_u32_e64 v50, s[8:9], s83, v120
	s_nop 1
	v_addc_co_u32_e64 v51, s[8:9], 0, v121, s[8:9]
	global_store_dword v[50:51], v52, off offset:1536
	v_mul_f32_e32 v52, 0xbfb8aa3b, v40
	v_exp_f32_e32 v52, v52
	s_nop 0
	v_add_f32_e32 v52, 1.0, v52
	v_rcp_f32_e32 v52, v52
	s_nop 0
	v_mul_f32_e32 v40, v40, v52
	v_mul_f32_e32 v40, v44, v40
	v_mul_f32_e32 v44, 0xbfb8aa3b, v41
	v_exp_f32_e32 v44, v44
	s_nop 0
	v_add_f32_e32 v44, 1.0, v44
	v_rcp_f32_e32 v44, v44
	s_nop 0
	v_mul_f32_e32 v41, v41, v44
	v_mul_f32_e32 v44, 0xbfb8aa3b, v42
	v_exp_f32_e32 v44, v44
	v_mul_f32_e32 v41, v45, v41
	v_add_f32_e32 v44, 1.0, v44
	v_rcp_f32_e32 v44, v44
	s_nop 0
	v_mul_f32_e32 v42, v42, v44
	v_mul_f32_e32 v44, 0xbfb8aa3b, v43
	v_exp_f32_e32 v44, v44
	v_mul_f32_e32 v42, v46, v42
	v_add_f32_e32 v44, 1.0, v44
	v_rcp_f32_e32 v44, v44
	s_nop 0
	v_mul_f32_e32 v43, v43, v44
	v_mul_f32_e32 v43, v47, v43
	v_cndmask_b32_e32 v44, v40, v42, vcc
	v_cndmask_b32_e32 v45, v41, v43, vcc
	s_nop 0
	v_mov_b32_dpp v44, v44 quad_perm:[1,0,3,2] row_mask:0xf bank_mask:0xf bound_ctrl:1
	v_mov_b32_dpp v45, v45 quad_perm:[1,0,3,2] row_mask:0xf bank_mask:0xf bound_ctrl:1
	v_cndmask_b32_e32 v42, v42, v44, vcc
	v_cndmask_b32_e32 v40, v44, v40, vcc
	v_cndmask_b32_e32 v43, v43, v45, vcc
	v_cndmask_b32_e32 v41, v45, v41, vcc
	v_cvt_pk_bf16_f32 v42, v40, v42
	v_add_co_u32_e64 v40, s[8:9], s84, v120
	v_cvt_pk_bf16_f32 v44, v41, v43
	s_nop 0
	v_addc_co_u32_e64 v41, s[8:9], 0, v121, s[8:9]
	global_store_dword v[40:41], v42, off
	v_add_co_u32_e64 v42, s[8:9], s85, v120
	s_nop 1
	v_addc_co_u32_e64 v43, s[8:9], 0, v121, s[8:9]
	global_store_dword v[42:43], v44, off offset:1536
	v_mul_f32_e32 v44, 0xbfb8aa3b, v32
	v_exp_f32_e32 v44, v44
	s_nop 0
	v_add_f32_e32 v44, 1.0, v44
	v_rcp_f32_e32 v44, v44
	s_nop 0
	v_mul_f32_e32 v32, v32, v44
	v_mul_f32_e32 v32, v36, v32
	v_mul_f32_e32 v36, 0xbfb8aa3b, v33
	v_exp_f32_e32 v36, v36
	s_nop 0
; template <class Epi>
; DI void gemm_tile(int ws, char* shmc, const TileDesc& td, Epi& epi, int pm, int pn, bool first, bool has_next, const TileDesc& tdn) {
;     ...
;   epi(pm, pn, acc, wr, wc, fr, fq);
;   asm volatile("s_waitcnt vmcnt(0)" ::: "memory");
;   __syncthreads();
; __global__ void __launch_bounds__(NTHR) fwd_kernel(Params pk) {
;     ...
;         auto epi = [&](int pm, int pn, Acc8& acc, int wr, int wc, int fr, int fq) {
; #pragma unroll
;           for (int ai = 0; ai < 2; ++ai)
; #pragma unroll
;             for (int bj = 0; bj < 2; ++bj)
; #pragma unroll
;               for (int m = 0; m < 4; ++m)
;                 {
;                   float v[4];
; #pragma unroll
;                   for (int j = 0; j < 4; ++j) {
;                     float a = acc[ai][bj][m][0][j], b = acc[ai][bj][m][1][j];
;                     v[j] = a * __builtin_amdgcn_rcpf(1.f + __expf(-a)) * b;
;                   }
;                   const long row0 = (long)pm * 256 + ai * 128 + wr * 64 + m * 16 + fq * 4;
;                   const int cole = pn * 128 + (bj * 4 + wc) * 16 + (fr & ~1);
;                   store_pair_bf16(act + row0 * DFF + cole, DFF, fr & 1, v[0], v[1], v[2], v[3]);
;                 }
;         };
	v_add_f32_e32 v36, 1.0, v36
	v_rcp_f32_e32 v36, v36
	s_nop 0
	v_mul_f32_e32 v33, v33, v36
	v_mul_f32_e32 v36, 0xbfb8aa3b, v34
	v_exp_f32_e32 v36, v36
	v_mul_f32_e32 v33, v37, v33
	v_add_f32_e32 v36, 1.0, v36
	v_rcp_f32_e32 v36, v36
	s_nop 0
	v_mul_f32_e32 v34, v34, v36
	v_mul_f32_e32 v36, 0xbfb8aa3b, v35
	v_exp_f32_e32 v36, v36
	v_mul_f32_e32 v34, v38, v34
	v_add_f32_e32 v36, 1.0, v36
	v_rcp_f32_e32 v36, v36
	s_nop 0
	v_mul_f32_e32 v35, v35, v36
	v_mul_f32_e32 v35, v39, v35
	v_cndmask_b32_e32 v36, v32, v34, vcc
	v_cndmask_b32_e32 v37, v33, v35, vcc
	s_nop 0
	v_mov_b32_dpp v36, v36 quad_perm:[1,0,3,2] row_mask:0xf bank_mask:0xf bound_ctrl:1
	v_mov_b32_dpp v37, v37 quad_perm:[1,0,3,2] row_mask:0xf bank_mask:0xf bound_ctrl:1
	v_cndmask_b32_e32 v34, v34, v36, vcc
	v_cndmask_b32_e32 v32, v36, v32, vcc
	v_cndmask_b32_e32 v35, v35, v37, vcc
	v_cndmask_b32_e32 v33, v37, v33, vcc
	v_cvt_pk_bf16_f32 v34, v32, v34
	v_add_co_u32_e64 v32, s[8:9], s86, v120
	v_cvt_pk_bf16_f32 v36, v33, v35
	s_nop 0
	v_addc_co_u32_e64 v33, s[8:9], 0, v121, s[8:9]
	global_store_dword v[32:33], v34, off
	v_add_co_u32_e64 v34, s[8:9], s87, v120
	s_nop 1
	v_addc_co_u32_e64 v35, s[8:9], 0, v121, s[8:9]
	global_store_dword v[34:35], v36, off offset:1536
	v_mul_f32_e32 v36, 0xbfb8aa3b, v24
	v_exp_f32_e32 v36, v36
	s_mov_b32 s8, s56
	v_add_f32_e32 v36, 1.0, v36
	v_rcp_f32_e32 v36, v36
	s_nop 0
	v_mul_f32_e32 v24, v24, v36
	v_mul_f32_e32 v24, v28, v24
	v_mul_f32_e32 v28, 0xbfb8aa3b, v25
	v_exp_f32_e32 v28, v28
	s_nop 0
	v_add_f32_e32 v28, 1.0, v28
	v_rcp_f32_e32 v28, v28
	s_nop 0
	v_mul_f32_e32 v25, v25, v28
	v_mul_f32_e32 v28, 0xbfb8aa3b, v26
	v_exp_f32_e32 v28, v28
	v_mul_f32_e32 v25, v29, v25
	v_add_f32_e32 v28, 1.0, v28
	v_rcp_f32_e32 v28, v28
	s_nop 0
	v_mul_f32_e32 v26, v26, v28
	v_mul_f32_e32 v28, 0xbfb8aa3b, v27
	v_exp_f32_e32 v28, v28
	v_mul_f32_e32 v26, v30, v26
	v_add_f32_e32 v28, 1.0, v28
	v_rcp_f32_e32 v28, v28
	s_nop 0
	v_mul_f32_e32 v27, v27, v28
	v_mul_f32_e32 v27, v31, v27
	v_cndmask_b32_e32 v28, v24, v26, vcc
	v_cndmask_b32_e32 v29, v25, v27, vcc
	s_nop 0
	v_mov_b32_dpp v28, v28 quad_perm:[1,0,3,2] row_mask:0xf bank_mask:0xf bound_ctrl:1
	v_mov_b32_dpp v29, v29 quad_perm:[1,0,3,2] row_mask:0xf bank_mask:0xf bound_ctrl:1
	v_cndmask_b32_e32 v26, v26, v28, vcc
	v_cndmask_b32_e32 v24, v28, v24, vcc
	v_cndmask_b32_e32 v27, v27, v29, vcc
	v_cndmask_b32_e32 v25, v29, v25, vcc
	v_cvt_pk_bf16_f32 v24, v24, v26
	v_cvt_pk_bf16_f32 v25, v25, v27
	global_store_dword v[56:57], v24, off offset:128
	global_store_dword v[58:59], v25, off offset:1664
	v_mul_f32_e32 v24, 0xbfb8aa3b, v16
	v_exp_f32_e32 v24, v24
	s_nop 0
	v_add_f32_e32 v24, 1.0, v24
	v_rcp_f32_e32 v24, v24
	s_nop 0
	v_mul_f32_e32 v16, v16, v24
	v_mul_f32_e32 v16, v20, v16
	v_mul_f32_e32 v20, 0xbfb8aa3b, v17
	v_exp_f32_e32 v20, v20
	s_nop 0
	v_add_f32_e32 v20, 1.0, v20
	v_rcp_f32_e32 v20, v20
	s_nop 0
	v_mul_f32_e32 v17, v17, v20
	v_mul_f32_e32 v20, 0xbfb8aa3b, v18
	v_exp_f32_e32 v20, v20
	v_mul_f32_e32 v17, v21, v17
	v_add_f32_e32 v20, 1.0, v20
	v_rcp_f32_e32 v20, v20
	s_nop 0
	v_mul_f32_e32 v18, v18, v20
	v_mul_f32_e32 v20, 0xbfb8aa3b, v19
	v_exp_f32_e32 v20, v20
	v_mul_f32_e32 v18, v22, v18
	v_add_f32_e32 v20, 1.0, v20
	v_rcp_f32_e32 v20, v20
	s_nop 0
	v_mul_f32_e32 v19, v19, v20
	v_mul_f32_e32 v19, v23, v19
	v_cndmask_b32_e32 v20, v16, v18, vcc
	v_cndmask_b32_e32 v21, v17, v19, vcc
	s_nop 0
	v_mov_b32_dpp v20, v20 quad_perm:[1,0,3,2] row_mask:0xf bank_mask:0xf bound_ctrl:1
	v_mov_b32_dpp v21, v21 quad_perm:[1,0,3,2] row_mask:0xf bank_mask:0xf bound_ctrl:1
	v_cndmask_b32_e32 v18, v18, v20, vcc
	v_cndmask_b32_e32 v16, v20, v16, vcc
	v_cndmask_b32_e32 v19, v19, v21, vcc
	v_cndmask_b32_e32 v17, v21, v17, vcc
	v_cvt_pk_bf16_f32 v16, v16, v18
	v_cvt_pk_bf16_f32 v17, v17, v19
	global_store_dword v[48:49], v16, off offset:128
	global_store_dword v[50:51], v17, off offset:1664
	v_mul_f32_e32 v16, 0xbfb8aa3b, v8
	v_exp_f32_e32 v16, v16
	s_nop 0
	v_add_f32_e32 v16, 1.0, v16
	v_rcp_f32_e32 v16, v16
	s_nop 0
	v_mul_f32_e32 v8, v8, v16
	v_mul_f32_e32 v8, v12, v8
	v_mul_f32_e32 v12, 0xbfb8aa3b, v9
	v_exp_f32_e32 v12, v12
	s_nop 0
	v_add_f32_e32 v12, 1.0, v12
	v_rcp_f32_e32 v12, v12
	s_nop 0
	v_mul_f32_e32 v9, v9, v12
	v_mul_f32_e32 v12, 0xbfb8aa3b, v10
	v_exp_f32_e32 v12, v12
	v_mul_f32_e32 v9, v13, v9
	v_add_f32_e32 v12, 1.0, v12
	v_rcp_f32_e32 v12, v12
	s_nop 0
	v_mul_f32_e32 v10, v10, v12
	v_mul_f32_e32 v12, 0xbfb8aa3b, v11
	v_exp_f32_e32 v12, v12
	v_mul_f32_e32 v10, v14, v10
	v_add_f32_e32 v12, 1.0, v12
	v_rcp_f32_e32 v12, v12
	s_nop 0
	v_mul_f32_e32 v11, v11, v12
	v_mul_f32_e32 v11, v15, v11
	v_cndmask_b32_e32 v12, v8, v10, vcc
	v_cndmask_b32_e32 v13, v9, v11, vcc
	s_nop 0
	v_mov_b32_dpp v12, v12 quad_perm:[1,0,3,2] row_mask:0xf bank_mask:0xf bound_ctrl:1
	v_mov_b32_dpp v13, v13 quad_perm:[1,0,3,2] row_mask:0xf bank_mask:0xf bound_ctrl:1
	v_cndmask_b32_e32 v10, v10, v12, vcc
	v_cndmask_b32_e32 v8, v12, v8, vcc
	v_cndmask_b32_e32 v11, v11, v13, vcc
	v_cndmask_b32_e32 v9, v13, v9, vcc
	v_cvt_pk_bf16_f32 v8, v8, v10
	v_cvt_pk_bf16_f32 v9, v9, v11
	global_store_dword v[40:41], v8, off offset:128
	global_store_dword v[42:43], v9, off offset:1664
	v_mul_f32_e32 v8, 0xbfb8aa3b, v0
	v_exp_f32_e32 v8, v8
	s_nop 0
	v_add_f32_e32 v8, 1.0, v8
	v_rcp_f32_e32 v8, v8
	s_nop 0
	v_mul_f32_e32 v0, v0, v8
	v_mul_f32_e32 v0, v4, v0
	v_mul_f32_e32 v4, 0xbfb8aa3b, v1
	v_exp_f32_e32 v4, v4
	s_nop 0
	v_add_f32_e32 v4, 1.0, v4
	v_rcp_f32_e32 v4, v4
	s_nop 0
	v_mul_f32_e32 v1, v1, v4
	v_mul_f32_e32 v4, 0xbfb8aa3b, v2
	v_exp_f32_e32 v4, v4
	v_mul_f32_e32 v1, v5, v1
	v_add_f32_e32 v4, 1.0, v4
	v_rcp_f32_e32 v4, v4
	s_nop 0
	v_mul_f32_e32 v2, v2, v4
	v_mul_f32_e32 v4, 0xbfb8aa3b, v3
	v_exp_f32_e32 v4, v4
	v_mul_f32_e32 v2, v6, v2
	v_add_f32_e32 v4, 1.0, v4
	v_rcp_f32_e32 v4, v4
	s_nop 0
	v_mul_f32_e32 v3, v3, v4
	v_mul_f32_e32 v3, v7, v3
	v_cndmask_b32_e32 v4, v0, v2, vcc
	v_cndmask_b32_e32 v5, v1, v3, vcc
	s_nop 0
	v_mov_b32_dpp v4, v4 quad_perm:[1,0,3,2] row_mask:0xf bank_mask:0xf bound_ctrl:1
	v_mov_b32_dpp v5, v5 quad_perm:[1,0,3,2] row_mask:0xf bank_mask:0xf bound_ctrl:1
	v_cndmask_b32_e32 v2, v2, v4, vcc
	v_cndmask_b32_e32 v0, v4, v0, vcc
	v_cndmask_b32_e32 v3, v3, v5, vcc
	v_cndmask_b32_e32 v1, v5, v1, vcc
	v_cvt_pk_bf16_f32 v0, v0, v2
	v_cvt_pk_bf16_f32 v1, v1, v3
	global_store_dword v[32:33], v0, off offset:128
	global_store_dword v[34:35], v1, off offset:1664
	s_nop 0
	s_andn2_b64 vcc, exec, s[62:63]
	s_waitcnt lgkmcnt(0)
	s_barrier
	s_cbranch_vccz .LBB0_162

; DI float dppx1(float v) { return __int_as_float(__builtin_amdgcn_update_dpp(0, __float_as_int(v), 0xB1, 0xF, 0xF, true)); }
; DI void store_pair_bf16(u16* base_even, long ld, bool odd, float v0, float v1, float v2, float v3) {
;   const float sx = odd ? v0 : v2, sy = odd ? v1 : v3;
;   const float rx = dppx1(sx), ry = dppx1(sy);
;   const uint32_t p0 = odd ? pack2(rx, v2) : pack2(v0, rx);
;   const uint32_t p1 = odd ? pack2(ry, v3) : pack2(v1, ry);
;   u16* q = base_even + (odd ? 2 * ld : 0);
;   *(uint32_t*)q = p0;
;   *(uint32_t*)(q + ld) = p1;
; }
; __global__ void __launch_bounds__(NTHR) fwd_kernel(Params pk) {
;     ...
;         auto epi = [&](int pm, int pn, Acc8& acc, int wr, int wc, int fr, int fq) {
; #pragma unroll
;           for (int ai = 0; ai < 2; ++ai)
; #pragma unroll
;             for (int bj = 0; bj < 2; ++bj)
; #pragma unroll
;               for (int m = 0; m < 4; ++m)
;                 {
;                   float v[4];
; #pragma unroll
;                   for (int j = 0; j < 4; ++j) {
;                     float a = acc[ai][bj][m][0][j], b = acc[ai][bj][m][1][j];
;                     v[j] = a * __builtin_amdgcn_rcpf(1.f + __expf(-a)) * b;
;                   }
;                   const long row0 = (long)pm * 256 + ai * 128 + wr * 64 + m * 16 + fq * 4;
;                   const int cole = pn * 128 + (bj * 4 + wc) * 16 + (fr & ~1);
;                   store_pair_bf16(act + row0 * DFF + cole, DFF, fr & 1, v[0], v[1], v[2], v[3]);
;                 }
;         };
.LBB0_946:
	s_ashr_i32 s63, s62, 31
	s_lshl_b64 s[4:5], s[62:63], 8
	v_ashrrev_i32_e32 v133, 31, v132
	v_lshl_add_u64 v[130:131], s[4:5], 0, v[132:133]
	s_lshl_b32 s3, s10, 7
	v_lshlrev_b32_e32 v128, 4, v146
	v_and_b32_e32 v132, 14, v138
	v_or3_b32 v132, v128, s3, v132
	v_and_b32_e32 v128, 1, v138
	v_bfe_i32 v133, v138, 0, 1
	v_cmp_eq_u32_e32 vcc, 0, v128
	v_and_b32_e32 v128, 0x2c00, v133
	v_lshl_add_u64 v[134:135], s[14:15], 0, v[128:129]
	v_mul_f32_e32 v128, 0xbfb8aa3b, v120
	v_exp_f32_e32 v128, v128
	v_ashrrev_i32_e32 v133, 31, v132
	v_lshl_or_b32 v130, v147, 2, v130
	v_lshl_add_u64 v[132:133], v[132:133], 1, v[134:135]
	v_add_f32_e32 v128, 1.0, v128
	v_rcp_f32_e32 v128, v128
	s_mov_b32 s3, 0x16000
	s_mov_b64 s[66:67], 0
	s_mov_b32 s62, s52
	v_mul_f32_e32 v120, v120, v128
	v_mul_f32_e32 v120, v124, v120
	v_mul_f32_e32 v124, 0xbfb8aa3b, v121
	v_exp_f32_e32 v124, v124
	s_nop 0
	v_add_f32_e32 v124, 1.0, v124
	v_rcp_f32_e32 v124, v124
	s_nop 0
	v_mul_f32_e32 v121, v121, v124
	v_mul_f32_e32 v124, 0xbfb8aa3b, v122
	v_exp_f32_e32 v124, v124
	v_mul_f32_e32 v121, v125, v121
	v_add_f32_e32 v124, 1.0, v124
	v_rcp_f32_e32 v124, v124
	s_nop 0
	v_mul_f32_e32 v122, v122, v124
	v_mul_f32_e32 v124, 0xbfb8aa3b, v123
	v_exp_f32_e32 v124, v124
	v_mul_f32_e32 v122, v126, v122
	v_add_f32_e32 v124, 1.0, v124
	v_rcp_f32_e32 v124, v124
	s_nop 0
	v_mul_f32_e32 v123, v123, v124
	v_mul_f32_e32 v123, v127, v123
	v_cndmask_b32_e32 v124, v120, v122, vcc
	v_cndmask_b32_e32 v125, v121, v123, vcc
	s_nop 0
	v_mov_b32_dpp v124, v124 quad_perm:[1,0,3,2] row_mask:0xf bank_mask:0xf bound_ctrl:1
	v_mov_b32_dpp v125, v125 quad_perm:[1,0,3,2] row_mask:0xf bank_mask:0xf bound_ctrl:1
	v_cndmask_b32_e32 v122, v122, v124, vcc
	v_cndmask_b32_e32 v120, v124, v120, vcc
	v_cndmask_b32_e32 v123, v123, v125, vcc
	v_cndmask_b32_e32 v121, v125, v121, vcc
	v_cvt_pk_bf16_f32 v124, v121, v123
	v_cvt_pk_bf16_f32 v122, v120, v122
	v_mad_u64_u32 v[120:121], s[4:5], v130, s70, v[132:133]
	v_mad_i32_i24 v121, v131, s70, v121
	global_store_dword v[120:121], v122, off
	v_add_co_u32_e64 v122, s[10:11], s9, v120
	s_nop 1
	v_addc_co_u32_e64 v123, s[10:11], 0, v121, s[10:11]
	global_store_dword v[122:123], v124, off offset:1536
	v_mul_f32_e32 v124, 0xbfb8aa3b, v112
	v_exp_f32_e32 v124, v124
	s_nop 0
	v_add_f32_e32 v124, 1.0, v124
	v_rcp_f32_e32 v124, v124
	s_nop 0
	v_mul_f32_e32 v112, v112, v124
	v_mul_f32_e32 v112, v116, v112
	v_mul_f32_e32 v116, 0xbfb8aa3b, v113
	v_exp_f32_e32 v116, v116
	s_nop 0
	v_add_f32_e32 v116, 1.0, v116
	v_rcp_f32_e32 v116, v116
	s_nop 0
	v_mul_f32_e32 v113, v113, v116
	v_mul_f32_e32 v116, 0xbfb8aa3b, v114
	v_exp_f32_e32 v116, v116
	v_mul_f32_e32 v113, v117, v113
	v_add_f32_e32 v116, 1.0, v116
	v_rcp_f32_e32 v116, v116
	s_nop 0
	v_mul_f32_e32 v114, v114, v116
	v_mul_f32_e32 v116, 0xbfb8aa3b, v115
	v_exp_f32_e32 v116, v116
	v_mul_f32_e32 v114, v118, v114
	v_add_f32_e32 v116, 1.0, v116
	v_rcp_f32_e32 v116, v116
	s_nop 0
	v_mul_f32_e32 v115, v115, v116
	v_mul_f32_e32 v115, v119, v115
	v_cndmask_b32_e32 v116, v112, v114, vcc
	v_cndmask_b32_e32 v117, v113, v115, vcc
	s_nop 0
	v_mov_b32_dpp v116, v116 quad_perm:[1,0,3,2] row_mask:0xf bank_mask:0xf bound_ctrl:1
	v_mov_b32_dpp v117, v117 quad_perm:[1,0,3,2] row_mask:0xf bank_mask:0xf bound_ctrl:1
	v_cndmask_b32_e32 v114, v114, v116, vcc
	v_cndmask_b32_e32 v112, v116, v112, vcc
	v_cndmask_b32_e32 v115, v115, v117, vcc
	v_cndmask_b32_e32 v113, v117, v113, vcc
	v_cvt_pk_bf16_f32 v114, v112, v114
	v_add_co_u32_e64 v112, s[10:11], s3, v120
	v_cvt_pk_bf16_f32 v116, v113, v115
	s_nop 0
	v_addc_co_u32_e64 v113, s[10:11], 0, v121, s[10:11]
	global_store_dword v[112:113], v114, off
	v_add_co_u32_e64 v114, s[10:11], s71, v120
	s_nop 1
	v_addc_co_u32_e64 v115, s[10:11], 0, v121, s[10:11]
	global_store_dword v[114:115], v116, off offset:1536
	v_mul_f32_e32 v116, 0xbfb8aa3b, v104
	v_exp_f32_e32 v116, v116
	s_nop 0
	v_add_f32_e32 v116, 1.0, v116
	v_rcp_f32_e32 v116, v116
	s_nop 0
	v_mul_f32_e32 v104, v104, v116
	v_mul_f32_e32 v104, v108, v104
	v_mul_f32_e32 v108, 0xbfb8aa3b, v105
	v_exp_f32_e32 v108, v108
	s_nop 0
	v_add_f32_e32 v108, 1.0, v108
	v_rcp_f32_e32 v108, v108
	s_nop 0
	v_mul_f32_e32 v105, v105, v108
	v_mul_f32_e32 v108, 0xbfb8aa3b, v106
	v_exp_f32_e32 v108, v108
	v_mul_f32_e32 v105, v109, v105
	v_add_f32_e32 v108, 1.0, v108
	v_rcp_f32_e32 v108, v108
	s_nop 0
	v_mul_f32_e32 v106, v106, v108
	v_mul_f32_e32 v108, 0xbfb8aa3b, v107
	v_exp_f32_e32 v108, v108
	v_mul_f32_e32 v106, v110, v106
	v_add_f32_e32 v108, 1.0, v108
	v_rcp_f32_e32 v108, v108
	s_nop 0
	v_mul_f32_e32 v107, v107, v108
	v_mul_f32_e32 v107, v111, v107
	v_cndmask_b32_e32 v108, v104, v106, vcc
	v_cndmask_b32_e32 v109, v105, v107, vcc
	s_nop 0
	v_mov_b32_dpp v108, v108 quad_perm:[1,0,3,2] row_mask:0xf bank_mask:0xf bound_ctrl:1
	v_mov_b32_dpp v109, v109 quad_perm:[1,0,3,2] row_mask:0xf bank_mask:0xf bound_ctrl:1
	v_cndmask_b32_e32 v106, v106, v108, vcc
	v_cndmask_b32_e32 v104, v108, v104, vcc
	v_cndmask_b32_e32 v107, v107, v109, vcc
	v_cndmask_b32_e32 v105, v109, v105, vcc
	v_cvt_pk_bf16_f32 v106, v104, v106
	v_add_co_u32_e64 v104, s[10:11], s72, v120
	v_cvt_pk_bf16_f32 v108, v105, v107
	s_nop 0
	v_addc_co_u32_e64 v105, s[10:11], 0, v121, s[10:11]
	global_store_dword v[104:105], v106, off
	v_add_co_u32_e64 v106, s[10:11], s73, v120
	s_nop 1
	v_addc_co_u32_e64 v107, s[10:11], 0, v121, s[10:11]
	global_store_dword v[106:107], v108, off offset:1536
	v_mul_f32_e32 v108, 0xbfb8aa3b, v96
	v_exp_f32_e32 v108, v108
	s_nop 0
	v_add_f32_e32 v108, 1.0, v108
	v_rcp_f32_e32 v108, v108
	s_nop 0
	v_mul_f32_e32 v96, v96, v108
	v_mul_f32_e32 v96, v100, v96
	v_mul_f32_e32 v100, 0xbfb8aa3b, v97
; DI float dppx1(float v) { return __int_as_float(__builtin_amdgcn_update_dpp(0, __float_as_int(v), 0xB1, 0xF, 0xF, true)); }
; DI void store_pair_bf16(u16* base_even, long ld, bool odd, float v0, float v1, float v2, float v3) {
;   const float sx = odd ? v0 : v2, sy = odd ? v1 : v3;
;   const float rx = dppx1(sx), ry = dppx1(sy);
;   const uint32_t p0 = odd ? pack2(rx, v2) : pack2(v0, rx);
;   const uint32_t p1 = odd ? pack2(ry, v3) : pack2(v1, ry);
;   u16* q = base_even + (odd ? 2 * ld : 0);
;   *(uint32_t*)q = p0;
;   *(uint32_t*)(q + ld) = p1;
; }
; __global__ void __launch_bounds__(NTHR) fwd_kernel(Params pk) {
;     ...
;         auto epi = [&](int pm, int pn, Acc8& acc, int wr, int wc, int fr, int fq) {
; #pragma unroll
;           for (int ai = 0; ai < 2; ++ai)
; #pragma unroll
;             for (int bj = 0; bj < 2; ++bj)
; #pragma unroll
;               for (int m = 0; m < 4; ++m)
;                 {
;                   float v[4];
; #pragma unroll
;                   for (int j = 0; j < 4; ++j) {
;                     float a = acc[ai][bj][m][0][j], b = acc[ai][bj][m][1][j];
;                     v[j] = a * __builtin_amdgcn_rcpf(1.f + __expf(-a)) * b;
;                   }
;                   const long row0 = (long)pm * 256 + ai * 128 + wr * 64 + m * 16 + fq * 4;
;                   const int cole = pn * 128 + (bj * 4 + wc) * 16 + (fr & ~1);
;                   store_pair_bf16(act + row0 * DFF + cole, DFF, fr & 1, v[0], v[1], v[2], v[3]);
;                 }
;         };
	v_exp_f32_e32 v100, v100
	s_nop 0
	v_add_f32_e32 v100, 1.0, v100
	v_rcp_f32_e32 v100, v100
	s_nop 0
	v_mul_f32_e32 v97, v97, v100
	v_mul_f32_e32 v100, 0xbfb8aa3b, v98
	v_exp_f32_e32 v100, v100
	v_mul_f32_e32 v97, v101, v97
	v_add_f32_e32 v100, 1.0, v100
	v_rcp_f32_e32 v100, v100
	s_nop 0
	v_mul_f32_e32 v98, v98, v100
	v_mul_f32_e32 v100, 0xbfb8aa3b, v99
	v_exp_f32_e32 v100, v100
	v_mul_f32_e32 v98, v102, v98
	v_add_f32_e32 v100, 1.0, v100
	v_rcp_f32_e32 v100, v100
	s_nop 0
	v_mul_f32_e32 v99, v99, v100
	v_mul_f32_e32 v99, v103, v99
	v_cndmask_b32_e32 v100, v96, v98, vcc
	v_cndmask_b32_e32 v101, v97, v99, vcc
	s_nop 0
	v_mov_b32_dpp v100, v100 quad_perm:[1,0,3,2] row_mask:0xf bank_mask:0xf bound_ctrl:1
	v_mov_b32_dpp v101, v101 quad_perm:[1,0,3,2] row_mask:0xf bank_mask:0xf bound_ctrl:1
	v_cndmask_b32_e32 v98, v98, v100, vcc
	v_cndmask_b32_e32 v96, v100, v96, vcc
	v_cndmask_b32_e32 v99, v99, v101, vcc
	v_cndmask_b32_e32 v97, v101, v97, vcc
	v_cvt_pk_bf16_f32 v98, v96, v98
	v_add_co_u32_e64 v96, s[10:11], s74, v120
	v_cvt_pk_bf16_f32 v100, v97, v99
	s_nop 0
	v_addc_co_u32_e64 v97, s[10:11], 0, v121, s[10:11]
	global_store_dword v[96:97], v98, off
	v_add_co_u32_e64 v98, s[10:11], s75, v120
	s_nop 1
	v_addc_co_u32_e64 v99, s[10:11], 0, v121, s[10:11]
	global_store_dword v[98:99], v100, off offset:1536
	v_mul_f32_e32 v100, 0xbfb8aa3b, v88
	v_exp_f32_e32 v100, v100
	s_nop 0
	v_add_f32_e32 v100, 1.0, v100
	v_rcp_f32_e32 v100, v100
	s_nop 0
	v_mul_f32_e32 v88, v88, v100
	v_mul_f32_e32 v88, v92, v88
	v_mul_f32_e32 v92, 0xbfb8aa3b, v89
	v_exp_f32_e32 v92, v92
	s_nop 0
	v_add_f32_e32 v92, 1.0, v92
	v_rcp_f32_e32 v92, v92
	s_nop 0
	v_mul_f32_e32 v89, v89, v92
	v_mul_f32_e32 v92, 0xbfb8aa3b, v90
	v_exp_f32_e32 v92, v92
	v_mul_f32_e32 v89, v93, v89
	v_add_f32_e32 v92, 1.0, v92
	v_rcp_f32_e32 v92, v92
	s_nop 0
	v_mul_f32_e32 v90, v90, v92
	v_mul_f32_e32 v92, 0xbfb8aa3b, v91
	v_exp_f32_e32 v92, v92
	v_mul_f32_e32 v90, v94, v90
	v_add_f32_e32 v92, 1.0, v92
	v_rcp_f32_e32 v92, v92
	s_nop 0
	v_mul_f32_e32 v91, v91, v92
	v_mul_f32_e32 v91, v95, v91
	v_cndmask_b32_e32 v92, v88, v90, vcc
	v_cndmask_b32_e32 v93, v89, v91, vcc
	s_nop 0
	v_mov_b32_dpp v92, v92 quad_perm:[1,0,3,2] row_mask:0xf bank_mask:0xf bound_ctrl:1
	v_mov_b32_dpp v93, v93 quad_perm:[1,0,3,2] row_mask:0xf bank_mask:0xf bound_ctrl:1
	v_cndmask_b32_e32 v90, v90, v92, vcc
	v_cndmask_b32_e32 v88, v92, v88, vcc
	v_cndmask_b32_e32 v91, v91, v93, vcc
	v_cndmask_b32_e32 v89, v93, v89, vcc
	v_cvt_pk_bf16_f32 v88, v88, v90
	v_cvt_pk_bf16_f32 v89, v89, v91
	global_store_dword v[120:121], v88, off offset:128
	global_store_dword v[122:123], v89, off offset:1664
	v_mul_f32_e32 v88, 0xbfb8aa3b, v80
	v_exp_f32_e32 v88, v88
	s_nop 0
	v_add_f32_e32 v88, 1.0, v88
	v_rcp_f32_e32 v88, v88
	s_nop 0
	v_mul_f32_e32 v80, v80, v88
	v_mul_f32_e32 v80, v84, v80
	v_mul_f32_e32 v84, 0xbfb8aa3b, v81
	v_exp_f32_e32 v84, v84
	s_nop 0
	v_add_f32_e32 v84, 1.0, v84
	v_rcp_f32_e32 v84, v84
	s_nop 0
	v_mul_f32_e32 v81, v81, v84
	v_mul_f32_e32 v84, 0xbfb8aa3b, v82
	v_exp_f32_e32 v84, v84
	v_mul_f32_e32 v81, v85, v81
	v_add_f32_e32 v84, 1.0, v84
	v_rcp_f32_e32 v84, v84
	s_nop 0
	v_mul_f32_e32 v82, v82, v84
	v_mul_f32_e32 v84, 0xbfb8aa3b, v83
	v_exp_f32_e32 v84, v84
	v_mul_f32_e32 v82, v86, v82
	v_add_f32_e32 v84, 1.0, v84
	v_rcp_f32_e32 v84, v84
	s_nop 0
	v_mul_f32_e32 v83, v83, v84
	v_mul_f32_e32 v83, v87, v83
	v_cndmask_b32_e32 v84, v80, v82, vcc
	v_cndmask_b32_e32 v85, v81, v83, vcc
	s_nop 0
	v_mov_b32_dpp v84, v84 quad_perm:[1,0,3,2] row_mask:0xf bank_mask:0xf bound_ctrl:1
	v_mov_b32_dpp v85, v85 quad_perm:[1,0,3,2] row_mask:0xf bank_mask:0xf bound_ctrl:1
	v_cndmask_b32_e32 v82, v82, v84, vcc
	v_cndmask_b32_e32 v80, v84, v80, vcc
	v_cndmask_b32_e32 v83, v83, v85, vcc
	v_cndmask_b32_e32 v81, v85, v81, vcc
	v_cvt_pk_bf16_f32 v80, v80, v82
	v_cvt_pk_bf16_f32 v81, v81, v83
	global_store_dword v[112:113], v80, off offset:128
	global_store_dword v[114:115], v81, off offset:1664
	v_mul_f32_e32 v80, 0xbfb8aa3b, v72
	v_exp_f32_e32 v80, v80
	s_nop 0
	v_add_f32_e32 v80, 1.0, v80
	v_rcp_f32_e32 v80, v80
	s_nop 0
	v_mul_f32_e32 v72, v72, v80
	v_mul_f32_e32 v72, v76, v72
	v_mul_f32_e32 v76, 0xbfb8aa3b, v73
	v_exp_f32_e32 v76, v76
	s_nop 0
	v_add_f32_e32 v76, 1.0, v76
	v_rcp_f32_e32 v76, v76
	s_nop 0
	v_mul_f32_e32 v73, v73, v76
	v_mul_f32_e32 v76, 0xbfb8aa3b, v74
	v_exp_f32_e32 v76, v76
	v_mul_f32_e32 v73, v77, v73
	v_add_f32_e32 v76, 1.0, v76
	v_rcp_f32_e32 v76, v76
	s_nop 0
	v_mul_f32_e32 v74, v74, v76
	v_mul_f32_e32 v76, 0xbfb8aa3b, v75
	v_exp_f32_e32 v76, v76
	v_mul_f32_e32 v74, v78, v74
	v_add_f32_e32 v76, 1.0, v76
	v_rcp_f32_e32 v76, v76
	s_nop 0
	v_mul_f32_e32 v75, v75, v76
	v_mul_f32_e32 v75, v79, v75
	v_cndmask_b32_e32 v76, v72, v74, vcc
	v_cndmask_b32_e32 v77, v73, v75, vcc
	s_nop 0
	v_mov_b32_dpp v76, v76 quad_perm:[1,0,3,2] row_mask:0xf bank_mask:0xf bound_ctrl:1
	v_mov_b32_dpp v77, v77 quad_perm:[1,0,3,2] row_mask:0xf bank_mask:0xf bound_ctrl:1
	v_cndmask_b32_e32 v74, v74, v76, vcc
	v_cndmask_b32_e32 v72, v76, v72, vcc
	v_cndmask_b32_e32 v75, v75, v77, vcc
	v_cndmask_b32_e32 v73, v77, v73, vcc
	v_cvt_pk_bf16_f32 v72, v72, v74
	v_cvt_pk_bf16_f32 v73, v73, v75
	global_store_dword v[104:105], v72, off offset:128
	global_store_dword v[106:107], v73, off offset:1664
	v_mul_f32_e32 v72, 0xbfb8aa3b, v64
	v_exp_f32_e32 v72, v72
	s_nop 0
	v_add_f32_e32 v72, 1.0, v72
	v_rcp_f32_e32 v72, v72
	s_nop 0
	v_mul_f32_e32 v64, v64, v72
	v_mul_f32_e32 v64, v68, v64
	v_mul_f32_e32 v68, 0xbfb8aa3b, v65
	v_exp_f32_e32 v68, v68
	s_nop 0
	v_add_f32_e32 v68, 1.0, v68
	v_rcp_f32_e32 v68, v68
	s_nop 0
	v_mul_f32_e32 v65, v65, v68
	v_mul_f32_e32 v68, 0xbfb8aa3b, v66
; DI float dppx1(float v) { return __int_as_float(__builtin_amdgcn_update_dpp(0, __float_as_int(v), 0xB1, 0xF, 0xF, true)); }
; DI void store_pair_bf16(u16* base_even, long ld, bool odd, float v0, float v1, float v2, float v3) {
;   const float sx = odd ? v0 : v2, sy = odd ? v1 : v3;
;   const float rx = dppx1(sx), ry = dppx1(sy);
;   const uint32_t p0 = odd ? pack2(rx, v2) : pack2(v0, rx);
;   const uint32_t p1 = odd ? pack2(ry, v3) : pack2(v1, ry);
;   u16* q = base_even + (odd ? 2 * ld : 0);
;   *(uint32_t*)q = p0;
;   *(uint32_t*)(q + ld) = p1;
; }
; __global__ void __launch_bounds__(NTHR) fwd_kernel(Params pk) {
;     ...
;         auto epi = [&](int pm, int pn, Acc8& acc, int wr, int wc, int fr, int fq) {
; #pragma unroll
;           for (int ai = 0; ai < 2; ++ai)
; #pragma unroll
;             for (int bj = 0; bj < 2; ++bj)
; #pragma unroll
;               for (int m = 0; m < 4; ++m)
;                 {
;                   float v[4];
; #pragma unroll
;                   for (int j = 0; j < 4; ++j) {
;                     float a = acc[ai][bj][m][0][j], b = acc[ai][bj][m][1][j];
;                     v[j] = a * __builtin_amdgcn_rcpf(1.f + __expf(-a)) * b;
;                   }
;                   const long row0 = (long)pm * 256 + ai * 128 + wr * 64 + m * 16 + fq * 4;
;                   const int cole = pn * 128 + (bj * 4 + wc) * 16 + (fr & ~1);
;                   store_pair_bf16(act + row0 * DFF + cole, DFF, fr & 1, v[0], v[1], v[2], v[3]);
;                 }
;         };
	v_exp_f32_e32 v68, v68
	v_mul_f32_e32 v65, v69, v65
	v_add_f32_e32 v68, 1.0, v68
	v_rcp_f32_e32 v68, v68
	s_nop 0
	v_mul_f32_e32 v66, v66, v68
	v_mul_f32_e32 v68, 0xbfb8aa3b, v67
	v_exp_f32_e32 v68, v68
	v_mul_f32_e32 v66, v70, v66
	v_add_f32_e32 v68, 1.0, v68
	v_rcp_f32_e32 v68, v68
	s_nop 0
	v_mul_f32_e32 v67, v67, v68
	v_mul_f32_e32 v67, v71, v67
	v_cndmask_b32_e32 v68, v64, v66, vcc
	v_cndmask_b32_e32 v69, v65, v67, vcc
	s_nop 0
	v_mov_b32_dpp v68, v68 quad_perm:[1,0,3,2] row_mask:0xf bank_mask:0xf bound_ctrl:1
	v_mov_b32_dpp v69, v69 quad_perm:[1,0,3,2] row_mask:0xf bank_mask:0xf bound_ctrl:1
	v_cndmask_b32_e32 v66, v66, v68, vcc
	v_cndmask_b32_e32 v64, v68, v64, vcc
	v_cndmask_b32_e32 v67, v67, v69, vcc
	v_cndmask_b32_e32 v65, v69, v65, vcc
	v_cvt_pk_bf16_f32 v64, v64, v66
	v_cvt_pk_bf16_f32 v65, v65, v67
	global_store_dword v[96:97], v64, off offset:128
	global_store_dword v[98:99], v65, off offset:1664
	v_mul_f32_e32 v64, 0xbfb8aa3b, v56
	v_exp_f32_e32 v64, v64
	s_nop 0
	v_add_f32_e32 v64, 1.0, v64
	v_rcp_f32_e32 v64, v64
	s_nop 0
	v_mul_f32_e32 v56, v56, v64
	v_mul_f32_e32 v56, v60, v56
	v_mul_f32_e32 v60, 0xbfb8aa3b, v57
	v_exp_f32_e32 v60, v60
	s_nop 0
	v_add_f32_e32 v60, 1.0, v60
	v_rcp_f32_e32 v60, v60
	s_nop 0
	v_mul_f32_e32 v57, v57, v60
	v_mul_f32_e32 v60, 0xbfb8aa3b, v58
	v_exp_f32_e32 v60, v60
	v_mul_f32_e32 v57, v61, v57
	v_add_f32_e32 v60, 1.0, v60
	v_rcp_f32_e32 v60, v60
	s_nop 0
	v_mul_f32_e32 v58, v58, v60
	v_mul_f32_e32 v60, 0xbfb8aa3b, v59
	v_exp_f32_e32 v60, v60
	v_mul_f32_e32 v58, v62, v58
	v_add_f32_e32 v60, 1.0, v60
	v_rcp_f32_e32 v60, v60
	s_nop 0
	v_mul_f32_e32 v59, v59, v60
	v_mul_f32_e32 v59, v63, v59
	v_cndmask_b32_e32 v60, v56, v58, vcc
	v_cndmask_b32_e32 v61, v57, v59, vcc
	s_nop 0
	v_mov_b32_dpp v60, v60 quad_perm:[1,0,3,2] row_mask:0xf bank_mask:0xf bound_ctrl:1
	v_mov_b32_dpp v61, v61 quad_perm:[1,0,3,2] row_mask:0xf bank_mask:0xf bound_ctrl:1
	v_cndmask_b32_e32 v58, v58, v60, vcc
	v_cndmask_b32_e32 v56, v60, v56, vcc
	v_cndmask_b32_e32 v59, v59, v61, vcc
	v_cndmask_b32_e32 v57, v61, v57, vcc
	v_cvt_pk_bf16_f32 v58, v56, v58
	v_add_co_u32_e64 v56, s[10:11], s76, v120
	v_cvt_pk_bf16_f32 v60, v57, v59
	s_nop 0
	v_addc_co_u32_e64 v57, s[10:11], 0, v121, s[10:11]
	global_store_dword v[56:57], v58, off
	v_add_co_u32_e64 v58, s[10:11], s77, v120
	s_nop 1
	v_addc_co_u32_e64 v59, s[10:11], 0, v121, s[10:11]
	global_store_dword v[58:59], v60, off offset:1536
	v_mul_f32_e32 v60, 0xbfb8aa3b, v48
	v_exp_f32_e32 v60, v60
	s_nop 0
	v_add_f32_e32 v60, 1.0, v60
	v_rcp_f32_e32 v60, v60
	s_nop 0
	v_mul_f32_e32 v48, v48, v60
	v_mul_f32_e32 v48, v52, v48
	v_mul_f32_e32 v52, 0xbfb8aa3b, v49
	v_exp_f32_e32 v52, v52
	s_nop 0
	v_add_f32_e32 v52, 1.0, v52
	v_rcp_f32_e32 v52, v52
	s_nop 0
	v_mul_f32_e32 v49, v49, v52
	v_mul_f32_e32 v52, 0xbfb8aa3b, v50
	v_exp_f32_e32 v52, v52
	v_mul_f32_e32 v49, v53, v49
	v_add_f32_e32 v52, 1.0, v52
	v_rcp_f32_e32 v52, v52
	s_nop 0
	v_mul_f32_e32 v50, v50, v52
	v_mul_f32_e32 v52, 0xbfb8aa3b, v51
	v_exp_f32_e32 v52, v52
	v_mul_f32_e32 v50, v54, v50
	v_add_f32_e32 v52, 1.0, v52
	v_rcp_f32_e32 v52, v52
	s_nop 0
	v_mul_f32_e32 v51, v51, v52
	v_mul_f32_e32 v51, v55, v51
	v_cndmask_b32_e32 v52, v48, v50, vcc
	v_cndmask_b32_e32 v53, v49, v51, vcc
	s_nop 0
	v_mov_b32_dpp v52, v52 quad_perm:[1,0,3,2] row_mask:0xf bank_mask:0xf bound_ctrl:1
	v_mov_b32_dpp v53, v53 quad_perm:[1,0,3,2] row_mask:0xf bank_mask:0xf bound_ctrl:1
	v_cndmask_b32_e32 v50, v50, v52, vcc
	v_cndmask_b32_e32 v48, v52, v48, vcc
	v_cndmask_b32_e32 v51, v51, v53, vcc
	v_cndmask_b32_e32 v49, v53, v49, vcc
	v_cvt_pk_bf16_f32 v50, v48, v50
	v_add_co_u32_e64 v48, s[10:11], s80, v120
	v_cvt_pk_bf16_f32 v52, v49, v51
	s_nop 0
	v_addc_co_u32_e64 v49, s[10:11], 0, v121, s[10:11]
	global_store_dword v[48:49], v50, off
	v_add_co_u32_e64 v50, s[10:11], s81, v120
	s_nop 1
	v_addc_co_u32_e64 v51, s[10:11], 0, v121, s[10:11]
	global_store_dword v[50:51], v52, off offset:1536
	v_mul_f32_e32 v52, 0xbfb8aa3b, v40
	v_exp_f32_e32 v52, v52
	s_nop 0
	v_add_f32_e32 v52, 1.0, v52
	v_rcp_f32_e32 v52, v52
	s_nop 0
	v_mul_f32_e32 v40, v40, v52
	v_mul_f32_e32 v40, v44, v40
	v_mul_f32_e32 v44, 0xbfb8aa3b, v41
	v_exp_f32_e32 v44, v44
	s_nop 0
	v_add_f32_e32 v44, 1.0, v44
	v_rcp_f32_e32 v44, v44
	s_nop 0
	v_mul_f32_e32 v41, v41, v44
	v_mul_f32_e32 v44, 0xbfb8aa3b, v42
	v_exp_f32_e32 v44, v44
	v_mul_f32_e32 v41, v45, v41
	v_add_f32_e32 v44, 1.0, v44
	v_rcp_f32_e32 v44, v44
	s_nop 0
	v_mul_f32_e32 v42, v42, v44
	v_mul_f32_e32 v44, 0xbfb8aa3b, v43
	v_exp_f32_e32 v44, v44
	v_mul_f32_e32 v42, v46, v42
	v_add_f32_e32 v44, 1.0, v44
	v_rcp_f32_e32 v44, v44
	s_nop 0
	v_mul_f32_e32 v43, v43, v44
	v_mul_f32_e32 v43, v47, v43
	v_cndmask_b32_e32 v44, v40, v42, vcc
	v_cndmask_b32_e32 v45, v41, v43, vcc
	s_nop 0
	v_mov_b32_dpp v44, v44 quad_perm:[1,0,3,2] row_mask:0xf bank_mask:0xf bound_ctrl:1
	v_mov_b32_dpp v45, v45 quad_perm:[1,0,3,2] row_mask:0xf bank_mask:0xf bound_ctrl:1
	v_cndmask_b32_e32 v42, v42, v44, vcc
	v_cndmask_b32_e32 v40, v44, v40, vcc
	v_cndmask_b32_e32 v43, v43, v45, vcc
	v_cndmask_b32_e32 v41, v45, v41, vcc
	v_cvt_pk_bf16_f32 v42, v40, v42
	v_add_co_u32_e64 v40, s[10:11], s82, v120
	v_cvt_pk_bf16_f32 v44, v41, v43
	s_nop 0
	v_addc_co_u32_e64 v41, s[10:11], 0, v121, s[10:11]
	global_store_dword v[40:41], v42, off
	v_add_co_u32_e64 v42, s[10:11], s83, v120
	s_nop 1
	v_addc_co_u32_e64 v43, s[10:11], 0, v121, s[10:11]
	global_store_dword v[42:43], v44, off offset:1536
	v_mul_f32_e32 v44, 0xbfb8aa3b, v32
	v_exp_f32_e32 v44, v44
	s_nop 0
	v_add_f32_e32 v44, 1.0, v44
	v_rcp_f32_e32 v44, v44
	s_nop 0
	v_mul_f32_e32 v32, v32, v44
	v_mul_f32_e32 v32, v36, v32
; template <class Epi>
; DI void gemm_tile(int ws, char* shmc, const TileDesc& td, Epi& epi, int pm, int pn, bool first, bool has_next, const TileDesc& tdn) {
;     ...
;   epi(pm, pn, acc, wr, wc, fr, fq);
;   asm volatile("s_waitcnt vmcnt(0)" ::: "memory");
;   __syncthreads();
; __global__ void __launch_bounds__(NTHR) fwd_kernel(Params pk) {
;     ...
;         auto epi = [&](int pm, int pn, Acc8& acc, int wr, int wc, int fr, int fq) {
; #pragma unroll
;           for (int ai = 0; ai < 2; ++ai)
; #pragma unroll
;             for (int bj = 0; bj < 2; ++bj)
; #pragma unroll
;               for (int m = 0; m < 4; ++m)
;                 {
;                   float v[4];
; #pragma unroll
;                   for (int j = 0; j < 4; ++j) {
;                     float a = acc[ai][bj][m][0][j], b = acc[ai][bj][m][1][j];
;                     v[j] = a * __builtin_amdgcn_rcpf(1.f + __expf(-a)) * b;
;                   }
;                   const long row0 = (long)pm * 256 + ai * 128 + wr * 64 + m * 16 + fq * 4;
;                   const int cole = pn * 128 + (bj * 4 + wc) * 16 + (fr & ~1);
;                   store_pair_bf16(act + row0 * DFF + cole, DFF, fr & 1, v[0], v[1], v[2], v[3]);
;                 }
;         };
	v_mul_f32_e32 v36, 0xbfb8aa3b, v33
	v_exp_f32_e32 v36, v36
	s_nop 0
	v_add_f32_e32 v36, 1.0, v36
	v_rcp_f32_e32 v36, v36
	s_nop 0
	v_mul_f32_e32 v33, v33, v36
	v_mul_f32_e32 v36, 0xbfb8aa3b, v34
	v_exp_f32_e32 v36, v36
	v_mul_f32_e32 v33, v37, v33
	v_add_f32_e32 v36, 1.0, v36
	v_rcp_f32_e32 v36, v36
	s_nop 0
	v_mul_f32_e32 v34, v34, v36
	v_mul_f32_e32 v36, 0xbfb8aa3b, v35
	v_exp_f32_e32 v36, v36
	v_mul_f32_e32 v34, v38, v34
	v_add_f32_e32 v36, 1.0, v36
	v_rcp_f32_e32 v36, v36
	s_nop 0
	v_mul_f32_e32 v35, v35, v36
	v_mul_f32_e32 v35, v39, v35
	v_cndmask_b32_e32 v36, v32, v34, vcc
	v_cndmask_b32_e32 v37, v33, v35, vcc
	s_nop 0
	v_mov_b32_dpp v36, v36 quad_perm:[1,0,3,2] row_mask:0xf bank_mask:0xf bound_ctrl:1
	v_mov_b32_dpp v37, v37 quad_perm:[1,0,3,2] row_mask:0xf bank_mask:0xf bound_ctrl:1
	v_cndmask_b32_e32 v34, v34, v36, vcc
	v_cndmask_b32_e32 v32, v36, v32, vcc
	v_cndmask_b32_e32 v35, v35, v37, vcc
	v_cndmask_b32_e32 v33, v37, v33, vcc
	v_cvt_pk_bf16_f32 v34, v32, v34
	v_add_co_u32_e64 v32, s[10:11], s84, v120
	v_cvt_pk_bf16_f32 v36, v33, v35
	s_nop 0
	v_addc_co_u32_e64 v33, s[10:11], 0, v121, s[10:11]
	global_store_dword v[32:33], v34, off
	v_add_co_u32_e64 v34, s[10:11], s85, v120
	s_nop 1
	v_addc_co_u32_e64 v35, s[10:11], 0, v121, s[10:11]
	global_store_dword v[34:35], v36, off offset:1536
	v_mul_f32_e32 v36, 0xbfb8aa3b, v24
	v_exp_f32_e32 v36, v36
	s_mov_b32 s10, s54
	v_add_f32_e32 v36, 1.0, v36
	v_rcp_f32_e32 v36, v36
	s_nop 0
	v_mul_f32_e32 v24, v24, v36
	v_mul_f32_e32 v24, v28, v24
	v_mul_f32_e32 v28, 0xbfb8aa3b, v25
	v_exp_f32_e32 v28, v28
	s_nop 0
	v_add_f32_e32 v28, 1.0, v28
	v_rcp_f32_e32 v28, v28
	s_nop 0
	v_mul_f32_e32 v25, v25, v28
	v_mul_f32_e32 v28, 0xbfb8aa3b, v26
	v_exp_f32_e32 v28, v28
	v_mul_f32_e32 v25, v29, v25
	v_add_f32_e32 v28, 1.0, v28
	v_rcp_f32_e32 v28, v28
	s_nop 0
	v_mul_f32_e32 v26, v26, v28
	v_mul_f32_e32 v28, 0xbfb8aa3b, v27
	v_exp_f32_e32 v28, v28
	v_mul_f32_e32 v26, v30, v26
	v_add_f32_e32 v28, 1.0, v28
	v_rcp_f32_e32 v28, v28
	s_nop 0
	v_mul_f32_e32 v27, v27, v28
	v_mul_f32_e32 v27, v31, v27
	v_cndmask_b32_e32 v28, v24, v26, vcc
	v_cndmask_b32_e32 v29, v25, v27, vcc
	s_nop 0
	v_mov_b32_dpp v28, v28 quad_perm:[1,0,3,2] row_mask:0xf bank_mask:0xf bound_ctrl:1
	v_mov_b32_dpp v29, v29 quad_perm:[1,0,3,2] row_mask:0xf bank_mask:0xf bound_ctrl:1
	v_cndmask_b32_e32 v26, v26, v28, vcc
	v_cndmask_b32_e32 v24, v28, v24, vcc
	v_cndmask_b32_e32 v27, v27, v29, vcc
	v_cndmask_b32_e32 v25, v29, v25, vcc
	v_cvt_pk_bf16_f32 v24, v24, v26
	v_cvt_pk_bf16_f32 v25, v25, v27
	global_store_dword v[56:57], v24, off offset:128
	global_store_dword v[58:59], v25, off offset:1664
	v_mul_f32_e32 v24, 0xbfb8aa3b, v16
	v_exp_f32_e32 v24, v24
	s_nop 0
	v_add_f32_e32 v24, 1.0, v24
	v_rcp_f32_e32 v24, v24
	s_nop 0
	v_mul_f32_e32 v16, v16, v24
	v_mul_f32_e32 v16, v20, v16
	v_mul_f32_e32 v20, 0xbfb8aa3b, v17
	v_exp_f32_e32 v20, v20
	s_nop 0
	v_add_f32_e32 v20, 1.0, v20
	v_rcp_f32_e32 v20, v20
	s_nop 0
	v_mul_f32_e32 v17, v17, v20
	v_mul_f32_e32 v20, 0xbfb8aa3b, v18
	v_exp_f32_e32 v20, v20
	v_mul_f32_e32 v17, v21, v17
	v_add_f32_e32 v20, 1.0, v20
	v_rcp_f32_e32 v20, v20
	s_nop 0
	v_mul_f32_e32 v18, v18, v20
	v_mul_f32_e32 v20, 0xbfb8aa3b, v19
	v_exp_f32_e32 v20, v20
	v_mul_f32_e32 v18, v22, v18
	v_add_f32_e32 v20, 1.0, v20
	v_rcp_f32_e32 v20, v20
	s_nop 0
	v_mul_f32_e32 v19, v19, v20
	v_mul_f32_e32 v19, v23, v19
	v_cndmask_b32_e32 v20, v16, v18, vcc
	v_cndmask_b32_e32 v21, v17, v19, vcc
	s_nop 0
	v_mov_b32_dpp v20, v20 quad_perm:[1,0,3,2] row_mask:0xf bank_mask:0xf bound_ctrl:1
	v_mov_b32_dpp v21, v21 quad_perm:[1,0,3,2] row_mask:0xf bank_mask:0xf bound_ctrl:1
	v_cndmask_b32_e32 v18, v18, v20, vcc
	v_cndmask_b32_e32 v16, v20, v16, vcc
	v_cndmask_b32_e32 v19, v19, v21, vcc
	v_cndmask_b32_e32 v17, v21, v17, vcc
	v_cvt_pk_bf16_f32 v16, v16, v18
	v_cvt_pk_bf16_f32 v17, v17, v19
	global_store_dword v[48:49], v16, off offset:128
	global_store_dword v[50:51], v17, off offset:1664
	v_mul_f32_e32 v16, 0xbfb8aa3b, v8
	v_exp_f32_e32 v16, v16
	s_nop 0
	v_add_f32_e32 v16, 1.0, v16
	v_rcp_f32_e32 v16, v16
	s_nop 0
	v_mul_f32_e32 v8, v8, v16
	v_mul_f32_e32 v8, v12, v8
	v_mul_f32_e32 v12, 0xbfb8aa3b, v9
	v_exp_f32_e32 v12, v12
	s_nop 0
	v_add_f32_e32 v12, 1.0, v12
	v_rcp_f32_e32 v12, v12
	s_nop 0
	v_mul_f32_e32 v9, v9, v12
	v_mul_f32_e32 v12, 0xbfb8aa3b, v10
	v_exp_f32_e32 v12, v12
	v_mul_f32_e32 v9, v13, v9
	v_add_f32_e32 v12, 1.0, v12
	v_rcp_f32_e32 v12, v12
	s_nop 0
	v_mul_f32_e32 v10, v10, v12
	v_mul_f32_e32 v12, 0xbfb8aa3b, v11
	v_exp_f32_e32 v12, v12
	v_mul_f32_e32 v10, v14, v10
	v_add_f32_e32 v12, 1.0, v12
	v_rcp_f32_e32 v12, v12
	s_nop 0
	v_mul_f32_e32 v11, v11, v12
	v_mul_f32_e32 v11, v15, v11
	v_cndmask_b32_e32 v12, v8, v10, vcc
	v_cndmask_b32_e32 v13, v9, v11, vcc
	s_nop 0
	v_mov_b32_dpp v12, v12 quad_perm:[1,0,3,2] row_mask:0xf bank_mask:0xf bound_ctrl:1
	v_mov_b32_dpp v13, v13 quad_perm:[1,0,3,2] row_mask:0xf bank_mask:0xf bound_ctrl:1
	v_cndmask_b32_e32 v10, v10, v12, vcc
	v_cndmask_b32_e32 v8, v12, v8, vcc
	v_cndmask_b32_e32 v11, v11, v13, vcc
	v_cndmask_b32_e32 v9, v13, v9, vcc
	v_cvt_pk_bf16_f32 v8, v8, v10
	v_cvt_pk_bf16_f32 v9, v9, v11
	global_store_dword v[40:41], v8, off offset:128
	global_store_dword v[42:43], v9, off offset:1664
	v_mul_f32_e32 v8, 0xbfb8aa3b, v0
	v_exp_f32_e32 v8, v8
	s_nop 0
	v_add_f32_e32 v8, 1.0, v8
	v_rcp_f32_e32 v8, v8
	s_nop 0
	v_mul_f32_e32 v0, v0, v8
	v_mul_f32_e32 v0, v4, v0
	v_mul_f32_e32 v4, 0xbfb8aa3b, v1
	v_exp_f32_e32 v4, v4
	s_nop 0
	v_add_f32_e32 v4, 1.0, v4
	v_rcp_f32_e32 v4, v4
	s_nop 0
	v_mul_f32_e32 v1, v1, v4
	v_mul_f32_e32 v4, 0xbfb8aa3b, v2
	v_exp_f32_e32 v4, v4
	v_mul_f32_e32 v1, v5, v1
	v_add_f32_e32 v4, 1.0, v4
	v_rcp_f32_e32 v4, v4
	s_nop 0
	v_mul_f32_e32 v2, v2, v4
	v_mul_f32_e32 v4, 0xbfb8aa3b, v3
	v_exp_f32_e32 v4, v4
	v_mul_f32_e32 v2, v6, v2
	v_add_f32_e32 v4, 1.0, v4
	v_rcp_f32_e32 v4, v4
	s_nop 0
	v_mul_f32_e32 v3, v3, v4
	v_mul_f32_e32 v3, v7, v3
	v_cndmask_b32_e32 v4, v0, v2, vcc
	v_cndmask_b32_e32 v5, v1, v3, vcc
	s_nop 0
	v_mov_b32_dpp v4, v4 quad_perm:[1,0,3,2] row_mask:0xf bank_mask:0xf bound_ctrl:1
	v_mov_b32_dpp v5, v5 quad_perm:[1,0,3,2] row_mask:0xf bank_mask:0xf bound_ctrl:1
	v_cndmask_b32_e32 v2, v2, v4, vcc
	v_cndmask_b32_e32 v0, v4, v0, vcc
	v_cndmask_b32_e32 v3, v3, v5, vcc
	v_cndmask_b32_e32 v1, v5, v1, vcc
	v_cvt_pk_bf16_f32 v0, v0, v2
	v_cvt_pk_bf16_f32 v1, v1, v3
	global_store_dword v[32:33], v0, off offset:128
	global_store_dword v[34:35], v1, off offset:1664
	s_nop 0
	s_andn2_b64 vcc, exec, s[60:61]
	s_waitcnt lgkmcnt(0)
	s_barrier
	s_cbranch_vccz .LBB0_965
